# v18 + dropped the L2/L1 invalidate (buffer_inv sc1) of 16 panel-counter acquires whose consumers read only single-assignment data since the last grid barrier (P3,P4,P5,P6a,P6b-start and layer-1 twins)
# speedup vs baseline: 1.0061x; 1.0021x over previous
;     __device__ __forceinline__ void a_ready(const Unit& u) const {
;     ...
;             __builtin_amdgcn_fence(__ATOMIC_ACQUIRE, "agent");
;             if (all && okflag != nullptr) *okflag = 1u;
;             asm volatile("s_waitcnt vmcnt(0) lgkmcnt(0)" ::: "memory");
.LBB0_284:
	s_waitcnt vmcnt(0) lgkmcnt(0)
	s_waitcnt vmcnt(0) lgkmcnt(0)

;     __device__ __forceinline__ void a_ready(const Unit& u) const {
;     ...
;                 all = __all(v >= need) != 0;
;                 if ((unsigned)__builtin_amdgcn_readlane((int)v, u.pm) >= need) break;
;                 if ((++polls & 255u) == 0u && __builtin_amdgcn_readfirstlane(__hip_atomic_load(tmo, __ATOMIC_RELAXED, __HIP_MEMORY_SCOPE_AGENT)) != 0u) break;
;                 if (__builtin_amdgcn_s_memrealtime() - t0 > 2000000ull) { __hip_atomic_store(tmo, 1u, __ATOMIC_RELAXED, __HIP_MEMORY_SCOPE_AGENT); break; }
;                 __builtin_amdgcn_s_sleep(2); }
;     ...
;             if (polls != 0u && ln == 0u) __hip_atomic_fetch_add(tmo + 32 + (PROBE_WAIT == 99 ? 0 : wslot), (unsigned)(__builtin_amdgcn_s_memrealtime() - t0), __ATOMIC_RELAXED, __HIP_MEMORY_SCOPE_AGENT);
;     ...
;             __builtin_amdgcn_fence(__ATOMIC_ACQUIRE, "agent");
;             if (all && okflag != nullptr) *okflag = 1u;
.LBB0_359:
	s_cmp_lg_u64 s[2:3], exec
	s_waitcnt vmcnt(0) lgkmcnt(0)
	s_cbranch_scc1 .LBB0_361
	s_add_i32 s0, 0, 0x24040
	v_mov_b32_e32 v1, 1
	v_mov_b32_e32 v2, s0
	ds_write_b32 v2, v1

;     __device__ __forceinline__ void a_ready(const Unit& u) const {
;     ...
;                 all = __all(v >= need) != 0;
;                 if ((unsigned)__builtin_amdgcn_readlane((int)v, u.pm) >= need) break;
;                 if ((++polls & 255u) == 0u && __builtin_amdgcn_readfirstlane(__hip_atomic_load(tmo, __ATOMIC_RELAXED, __HIP_MEMORY_SCOPE_AGENT)) != 0u) break;
;                 if (__builtin_amdgcn_s_memrealtime() - t0 > 2000000ull) { __hip_atomic_store(tmo, 1u, __ATOMIC_RELAXED, __HIP_MEMORY_SCOPE_AGENT); break; }
;                 __builtin_amdgcn_s_sleep(2); }
;     ...
;             if (polls != 0u && ln == 0u) __hip_atomic_fetch_add(tmo + 32 + (PROBE_WAIT == 99 ? 0 : wslot), (unsigned)(__builtin_amdgcn_s_memrealtime() - t0), __ATOMIC_RELAXED, __HIP_MEMORY_SCOPE_AGENT);
;     ...
;             __builtin_amdgcn_fence(__ATOMIC_ACQUIRE, "agent");
;             if (all && okflag != nullptr) *okflag = 1u;
.LBB0_386:
	s_cmp_lg_u64 s[0:1], exec
	s_waitcnt vmcnt(0) lgkmcnt(0)
	s_cbranch_scc1 .LBB0_388
	v_mov_b32_e32 v128, s91
	ds_write_b32 v128, v242

; __device__ __forceinline__ void conv_fix_phase(bf16* ACT, const float* HALO, const float* PEND, const float* cw, const float* cb, const unsigned* upcnt, unsigned upneed, unsigned* convcnt, unsigned* tmo, ...
;     ...
;             __builtin_amdgcn_fence(__ATOMIC_ACQUIRE, "agent");
;             asm volatile("s_waitcnt vmcnt(0)" ::: "memory");
.LBB0_487:
	s_waitcnt vmcnt(0) lgkmcnt(0)
	s_waitcnt vmcnt(0)

;     __device__ __forceinline__ void a_ready(const Unit& u) const {
;     ...
;                 all = __all(v >= need) != 0;
;                 if ((unsigned)__builtin_amdgcn_readlane((int)v, u.pm) >= need) break;
;                 if ((++polls & 255u) == 0u && __builtin_amdgcn_readfirstlane(__hip_atomic_load(tmo, __ATOMIC_RELAXED, __HIP_MEMORY_SCOPE_AGENT)) != 0u) break;
;                 if (__builtin_amdgcn_s_memrealtime() - t0 > 2000000ull) { __hip_atomic_store(tmo, 1u, __ATOMIC_RELAXED, __HIP_MEMORY_SCOPE_AGENT); break; }
;                 __builtin_amdgcn_s_sleep(2); }
;     ...
;             if (polls != 0u && ln == 0u) __hip_atomic_fetch_add(tmo + 32 + (PROBE_WAIT == 99 ? 0 : wslot), (unsigned)(__builtin_amdgcn_s_memrealtime() - t0), __ATOMIC_RELAXED, __HIP_MEMORY_SCOPE_AGENT);
;     ...
;             __builtin_amdgcn_fence(__ATOMIC_ACQUIRE, "agent");
;             if (all && okflag != nullptr) *okflag = 1u;
.LBB0_1068:
	s_cmp_lg_u64 s[2:3], exec
	s_waitcnt vmcnt(0) lgkmcnt(0)
	s_cbranch_scc1 .LBB0_1070
	s_add_i32 s0, 0, 0x24044
	v_mov_b32_e32 v1, 1
	v_mov_b32_e32 v2, s0
	ds_write_b32 v2, v1

;     __device__ __forceinline__ void a_ready(const Unit& u) const {
;     ...
;                 all = __all(v >= need) != 0;
;                 if ((unsigned)__builtin_amdgcn_readlane((int)v, u.pm) >= need) break;
;                 if ((++polls & 255u) == 0u && __builtin_amdgcn_readfirstlane(__hip_atomic_load(tmo, __ATOMIC_RELAXED, __HIP_MEMORY_SCOPE_AGENT)) != 0u) break;
;                 if (__builtin_amdgcn_s_memrealtime() - t0 > 2000000ull) { __hip_atomic_store(tmo, 1u, __ATOMIC_RELAXED, __HIP_MEMORY_SCOPE_AGENT); break; }
;                 __builtin_amdgcn_s_sleep(2); }
;     ...
;             if (polls != 0u && ln == 0u) __hip_atomic_fetch_add(tmo + 32 + (PROBE_WAIT == 99 ? 0 : wslot), (unsigned)(__builtin_amdgcn_s_memrealtime() - t0), __ATOMIC_RELAXED, __HIP_MEMORY_SCOPE_AGENT);
;     ...
;             __builtin_amdgcn_fence(__ATOMIC_ACQUIRE, "agent");
;             if (all && okflag != nullptr) *okflag = 1u;
.LBB0_1095:
	s_cmp_lg_u64 s[10:11], exec
	s_waitcnt vmcnt(0) lgkmcnt(0)
	s_cbranch_scc1 .LBB0_1097
	v_mov_b32_e32 v128, s48
	ds_write_b32 v128, v246
